# up-GEMM main loop: one static s_setprio 1 for the leading half-workgroup (waves 0-3) at phase entry, the 16 per-block priority flips in the K loop deleted, back to 0 at phase exit (raising the trailin
# speedup vs baseline: 1.0131x; 1.0027x over previous
; #define PG8_STAGE(bufoff, gbase, voff) do { _Pragma("unroll") for (int _i = 0; _i < 2; ++_i) \
;         __builtin_amdgcn_global_load_lds((const unsigned*)((const char*)(gbase) + (voff)[_i]), (PG8_LAS unsigned*)(lds + (bufoff) + ldsw + _i * 8192), 16, 0, 0); } while (0)
; #define PG8_WAIT_V(n) asm volatile("s_waitcnt vmcnt(" #n ")" ::: "memory")
; #define PG8_BAR __builtin_amdgcn_s_barrier()
; template <class Epi, class Sched, bool ALIGN_EPI = false, bool SP2 = false>
; __device__ __forceinline__ void gemm_phase(PG8_LAS unsigned char* lds, const Gemm g, const Sched& S, const Epi& E) {
;     ...
;     for (int i = 0; i < 2; ++i) { int R, C; stage_rc(tid * 16 + i * 8192, R, C); const int Rb = Epi::PERM ? ((R & ~31) + perm32(R & 31)) : R;
;         voffA[i] = (unsigned)(R * K + C) * 2u; voffB[i] = (unsigned)(Rb * K + C) * 2u; }
;     const size_t kstep = (size_t)(BK * 2);
;     const size_t hstep = (size_t)HALF * K * 2;
;     const size_t tstep = 2 * hstep;
;     const unsigned ldsw = (unsigned)wid * 1024u;
;     const int aoff = lds_byte(wr * 64 + fr, fq * 8), boff = lds_byte(wc * 32 + fr, fq * 8);
;     ...
;         PG8_STAGE(PG8_SB(0, 0), cB, voffB); PG8_STAGE(PG8_SB(0, 1), cB + hstep, voffB); PG8_STAGE(PG8_SA(0, 0), cA, voffA); PG8_STAGE(PG8_SA(0, 1), cA + hstep, voffA);
;         if (wr == 1) PG8_BAR;
;         PG8_WAIT_V(2); PG8_BAR;
;         PG8_STAGE(PG8_SB(1, 0), cB + kstep, voffB); PG8_STAGE(PG8_SA(1, 0), cA + kstep, voffA); PG8_STAGE(PG8_SB(1, 1), cB + hstep + kstep, voffB);
;         PG8_WAIT_V(6); PG8_BAR;
.LBB0_155:
	v_readlane_b32 s22, v254, 14
	v_mov_b32_e32 v135, v193
	v_readlane_b32 s23, v254, 15
	s_and_b32 s8, s8, 3
	s_add_i32 m0, s31, 0x18000
	v_lshl_add_u64 v[0:1], v[0:1], 0, s[0:1]
	v_lshl_add_u64 v[12:13], s[22:23], 0, v[134:135]
	v_mov_b32_e32 v131, v193
	s_lshl_b32 s9, s7, 13
	s_lshl_b32 s16, s8, 12
	s_waitcnt vmcnt(2)
	s_barrier
	global_load_lds_dwordx4 v[0:1], off
	v_lshl_add_u64 v[0:1], v[2:3], 0, s[0:1]
	s_add_i32 m0, s31, 0x1a000
	s_add_i32 s37, s31, 0x8000
	s_add_i32 s38, s31, 0xa000
	v_lshl_add_u64 v[14:15], s[22:23], 0, v[130:131]
	global_load_lds_dwordx4 v[0:1], off
	v_lshl_add_u64 v[0:1], v[12:13], 0, s[0:1]
	s_mov_b32 m0, s37
	s_add_u32 s4, s26, 0x40080
	global_load_lds_dwordx4 v[0:1], off
	v_lshl_add_u64 v[0:1], v[14:15], 0, s[0:1]
	s_mov_b32 m0, s38
	s_addc_u32 s5, s27, 0
	global_load_lds_dwordx4 v[0:1], off
	s_add_i32 m0, s31, 0x1c000
	v_lshl_add_u64 v[0:1], s[4:5], 0, v[132:133]
	global_load_lds_dwordx4 v[0:1], off
	v_lshl_add_u64 v[0:1], s[4:5], 0, v[128:129]
	s_add_i32 m0, s31, 0x1e000
	s_cmpk_lt_u32 s6, 0x100
	global_load_lds_dwordx4 v[0:1], off
	v_bfe_u32 v1, v4, 4, 2
	v_and_b32_e32 v0, 15, v4
	v_lshlrev_b32_e32 v3, 4, v1
	v_lshl_or_b32 v141, s7, 6, v0
	v_lshl_or_b32 v3, v0, 6, v3
	v_lshlrev_b32_e32 v0, 2, v0
	v_and_b32_e32 v11, 32, v0
	v_bitop3_b32 v148, v3, s16, v11 bitop3:0xde
	s_cselect_b64 s[16:17], -1, 0
	s_lshl_b32 s4, s7, 2
	s_or_b32 s4, s4, s8
	s_mulk_i32 s4, 0x210
	s_add_i32 s40, s4, 0
	s_add_i32 s40, s40, 0x21000
	v_add_u32_e32 v152, s40, v0
	v_lshlrev_b32_e32 v0, 14, v9
	v_and_b32_e32 v0, 0xffff8000, v0
	v_lshlrev_b32_e32 v2, 3, v1
	v_lshlrev_b32_e32 v150, 6, v1
	v_lshl_add_u32 v0, v8, 11, v0
	v_and_b32_e32 v1, 1, v9
	v_lshl_or_b32 v0, v1, 6, v0
	v_lshl_add_u32 v136, v10, 1, v0
	v_lshlrev_b32_e32 v0, 14, v5
	v_and_b32_e32 v0, 0xffff8000, v0
	s_waitcnt vmcnt(6)
	v_lshl_add_u32 v0, v6, 11, v0
	v_and_b32_e32 v1, 1, v5
	v_bitop3_b32 v12, v3, s9, v11 bitop3:0xde
	v_lshl_or_b32 v149, s8, 5, v2
	v_and_b32_e32 v2, 63, v4
	v_lshl_or_b32 v0, v1, 6, v0
	v_readlane_b32 s4, v254, 12
	s_mov_b32 s39, 0
	v_cmp_eq_u32_e64 s[6:7], 0, v2
	v_lshl_add_u32 v151, v2, 2, s40
	v_mov_b32_e32 v137, v193
	v_lshl_add_u32 v138, v7, 1, v0
	v_mov_b32_e32 v139, v193
	v_add_u32_e32 v153, 0, v12
	v_readlane_b32 s41, v254, 9
	s_mov_b32 s42, s4
	s_mov_b64 s[8:9], s[22:23]
	s_barrier
	v_readlane_b32 s5, v254, 13
	v_readlane_b32 s33, v252, 0
	s_cmp_lt_u32 s33, 4
	s_cbranch_scc0 .Lprio_up_done
	s_setprio 1
.Lprio_up_done:
	s_branch .LBB0_158
.LBB0_156:
	s_mov_b64 s[4:5], 0

; #define PG8_STAGE(bufoff, gbase, voff) do { _Pragma("unroll") for (int _i = 0; _i < 2; ++_i) \
;         __builtin_amdgcn_global_load_lds((const unsigned*)((const char*)(gbase) + (voff)[_i]), (PG8_LAS unsigned*)(lds + (bufoff) + ldsw + _i * 8192), 16, 0, 0); } while (0)
; #define PG8_LDA(dst, b, h) do { _Pragma("unroll") for (int m = 0; m < 4; ++m) _Pragma("unroll") for (int k = 0; k < 2; ++k) dst[m][k] = *(const PG8_LAS bf16x8*)(lds + PG8_SA(b, h) + aoff + m * 2048 + k * 1024); } while (0)
; #define PG8_LDB(dst, b, h) do { _Pragma("unroll") for (int n = 0; n < 2; ++n) _Pragma("unroll") for (int k = 0; k < 2; ++k) dst[n][k] = *(const PG8_LAS bf16x8*)(lds + PG8_SB(b, h) + boff + n * 2048 + k * 1024); } while (0)
; #define PG8_MMA(ai, bj, At, Bt) do { __builtin_amdgcn_s_setprio(1); _Pragma("unroll") for (int m = 0; m < 4; ++m) _Pragma("unroll") for (int n = 0; n < 2; ++n) _Pragma("unroll") for (int k = 0; k < 2; ++k) \
;         acc[ai][bj][m][n] = __builtin_amdgcn_mfma_f32_16x16x32_bf16(Bt[n][k], At[m][k], acc[ai][bj][m][n], 0, 0, 0); __builtin_amdgcn_s_setprio(0); } while (0)
; #define PG8_WAIT_V(n) asm volatile("s_waitcnt vmcnt(" #n ")" ::: "memory")
; #define PG8_WAIT_L(n) asm volatile("s_waitcnt lgkmcnt(" #n ")" ::: "memory")
; #define PG8_BAR __builtin_amdgcn_s_barrier()
; #define PG8_SCHED __builtin_amdgcn_sched_barrier(0)
; template <class Epi, class Sched, bool ALIGN_EPI = false, bool SP2 = false>
; __device__ __forceinline__ void gemm_phase(PG8_LAS unsigned char* lds, const Gemm g, const Sched& S, const Epi& E) {
;     ...
;             PG8_LDB(B0, 0, 0); PG8_LDB(B1, 0, 1); PG8_SCHED; PG8_LDA(At, 0, 0); PG8_STAGE(PG8_SA(1, 1), a1 + hstep, voffA);
;             PG8_WAIT_V(8); PG8_WAIT_L(0); PG8_BAR; PG8_MMA(0, 0, At, B0); PG8_MMA(0, 1, At, B1); PG8_BAR; PG8_SCHED;
.LBB0_161:
	s_add_u32 s26, s8, 0xfffc0080
	s_addc_u32 s27, s9, -1
	s_add_i32 s48, 0, 0x10000
	s_cmp_eq_u32 s47, 12
	s_cselect_b32 s29, s21, s27
	s_cselect_b32 s28, s43, s26
	v_add_u32_e32 v140, s48, v148
	s_cselect_b32 s27, s19, s46
	s_cselect_b32 s26, s44, s45
	s_add_i32 s50, 0, 0x14000
	ds_read_b128 v[142:145], v140
	ds_read_b128 v[154:157], v140 offset:1024
	ds_read_b128 v[158:161], v140 offset:2048
	ds_read_b128 v[162:165], v140 offset:3072
	v_add_u32_e32 v140, s50, v148
	ds_read_b128 v[166:169], v140
	ds_read_b128 v[170:173], v140 offset:1024
	ds_read_b128 v[174:177], v140 offset:2048
	ds_read_b128 v[178:181], v140 offset:3072
	v_lshl_add_u64 v[146:147], s[8:9], 0, v[136:137]
	s_add_i32 m0, s31, 0xc000
	ds_read_b128 v[182:185], v153
	ds_read_b128 v[186:189], v153 offset:1024
	ds_read_b128 v[202:205], v153 offset:2048
	ds_read_b128 v[206:209], v153 offset:3072
	ds_read_b128 v[210:213], v153 offset:4096
	ds_read_b128 v[214:217], v153 offset:5120
	ds_read_b128 v[232:235], v153 offset:6144
	ds_read_b128 v[236:239], v153 offset:7168
	global_load_lds_dwordx4 v[146:147], off
	v_lshl_add_u64 v[146:147], s[8:9], 0, v[138:139]
	s_add_i32 m0, s31, 0xe000
	s_nop 0
	global_load_lds_dwordx4 v[146:147], off
	s_waitcnt vmcnt(8)
	s_waitcnt lgkmcnt(0)
	s_barrier

; #define PG8_MMA(ai, bj, At, Bt) do { __builtin_amdgcn_s_setprio(1); _Pragma("unroll") for (int m = 0; m < 4; ++m) _Pragma("unroll") for (int n = 0; n < 2; ++n) _Pragma("unroll") for (int k = 0; k < 2; ++k) \
;         acc[ai][bj][m][n] = __builtin_amdgcn_mfma_f32_16x16x32_bf16(Bt[n][k], At[m][k], acc[ai][bj][m][n], 0, 0, 0); __builtin_amdgcn_s_setprio(0); } while (0)
; #define PG8_WAIT_V(n) asm volatile("s_waitcnt vmcnt(" #n ")" ::: "memory")
; #define PG8_WAIT_L(n) asm volatile("s_waitcnt lgkmcnt(" #n ")" ::: "memory")
; #define PG8_BAR __builtin_amdgcn_s_barrier()
; #define PG8_SCHED __builtin_amdgcn_sched_barrier(0)
; template <class Epi, class Sched, bool ALIGN_EPI = false, bool SP2 = false>
; __device__ __forceinline__ void gemm_phase(PG8_LAS unsigned char* lds, const Gemm g, const Sched& S, const Epi& E) {
;     ...
;             PG8_WAIT_V(8); PG8_WAIT_L(0); PG8_BAR; PG8_MMA(0, 0, At, B0); PG8_MMA(0, 1, At, B1); PG8_BAR; PG8_SCHED;
	s_waitcnt lgkmcnt(0)
	v_mfma_f32_16x16x32_bf16 v[124:127], v[142:145], v[182:185], v[124:127]
	v_mfma_f32_16x16x32_bf16 v[116:119], v[158:161], v[182:185], v[116:119]
	v_mfma_f32_16x16x32_bf16 v[108:111], v[142:145], v[202:205], v[108:111]
	v_mfma_f32_16x16x32_bf16 v[100:103], v[158:161], v[202:205], v[100:103]
	v_mfma_f32_16x16x32_bf16 v[92:95], v[142:145], v[210:213], v[92:95]
	v_mfma_f32_16x16x32_bf16 v[84:87], v[158:161], v[210:213], v[84:87]
	v_mfma_f32_16x16x32_bf16 v[76:79], v[142:145], v[232:235], v[76:79]
	v_mfma_f32_16x16x32_bf16 v[68:71], v[158:161], v[232:235], v[68:71]
	v_mfma_f32_16x16x32_bf16 v[124:127], v[154:157], v[186:189], v[124:127]
	v_mfma_f32_16x16x32_bf16 v[116:119], v[162:165], v[186:189], v[116:119]
	v_mfma_f32_16x16x32_bf16 v[108:111], v[154:157], v[206:209], v[108:111]
	v_mfma_f32_16x16x32_bf16 v[100:103], v[162:165], v[206:209], v[100:103]
	v_mfma_f32_16x16x32_bf16 v[92:95], v[154:157], v[214:217], v[92:95]
	v_mfma_f32_16x16x32_bf16 v[84:87], v[162:165], v[214:217], v[84:87]
	v_mfma_f32_16x16x32_bf16 v[76:79], v[154:157], v[236:239], v[76:79]
	v_mfma_f32_16x16x32_bf16 v[68:71], v[162:165], v[236:239], v[68:71]


; #define PG8_MMA(ai, bj, At, Bt) do { __builtin_amdgcn_s_setprio(1); _Pragma("unroll") for (int m = 0; m < 4; ++m) _Pragma("unroll") for (int n = 0; n < 2; ++n) _Pragma("unroll") for (int k = 0; k < 2; ++k) \
;         acc[ai][bj][m][n] = __builtin_amdgcn_mfma_f32_16x16x32_bf16(Bt[n][k], At[m][k], acc[ai][bj][m][n], 0, 0, 0); __builtin_amdgcn_s_setprio(0); } while (0)
; #define PG8_WAIT_V(n) asm volatile("s_waitcnt vmcnt(" #n ")" ::: "memory")
; #define PG8_WAIT_L(n) asm volatile("s_waitcnt lgkmcnt(" #n ")" ::: "memory")
; #define PG8_BAR __builtin_amdgcn_s_barrier()
; #define PG8_SCHED __builtin_amdgcn_sched_barrier(0)
; template <class Epi, class Sched, bool ALIGN_EPI = false, bool SP2 = false>
; __device__ __forceinline__ void gemm_phase(PG8_LAS unsigned char* lds, const Gemm g, const Sched& S, const Epi& E) {
;     ...
;             PG8_WAIT_V(8); PG8_WAIT_L(0); PG8_BAR; PG8_MMA(0, 0, At, B0); PG8_MMA(0, 1, At, B1); PG8_BAR; PG8_SCHED;
	v_mfma_f32_16x16x32_bf16 v[120:123], v[166:169], v[182:185], v[120:123]
	v_mfma_f32_16x16x32_bf16 v[112:115], v[174:177], v[182:185], v[112:115]
	v_mfma_f32_16x16x32_bf16 v[104:107], v[166:169], v[202:205], v[104:107]
	v_mfma_f32_16x16x32_bf16 v[96:99], v[174:177], v[202:205], v[96:99]
	v_mfma_f32_16x16x32_bf16 v[88:91], v[166:169], v[210:213], v[88:91]
	v_mfma_f32_16x16x32_bf16 v[80:83], v[174:177], v[210:213], v[80:83]
	v_mfma_f32_16x16x32_bf16 v[72:75], v[166:169], v[232:235], v[72:75]
	v_mfma_f32_16x16x32_bf16 v[64:67], v[174:177], v[232:235], v[64:67]
	v_mfma_f32_16x16x32_bf16 v[120:123], v[170:173], v[186:189], v[120:123]
	v_mfma_f32_16x16x32_bf16 v[112:115], v[178:181], v[186:189], v[112:115]
	v_mfma_f32_16x16x32_bf16 v[104:107], v[170:173], v[206:209], v[104:107]
	v_mfma_f32_16x16x32_bf16 v[96:99], v[178:181], v[206:209], v[96:99]
	v_mfma_f32_16x16x32_bf16 v[88:91], v[170:173], v[214:217], v[88:91]
	v_mfma_f32_16x16x32_bf16 v[80:83], v[178:181], v[214:217], v[80:83]
	v_mfma_f32_16x16x32_bf16 v[72:75], v[170:173], v[236:239], v[72:75]
	v_mfma_f32_16x16x32_bf16 v[64:67], v[178:181], v[236:239], v[64:67]

; #define PG8_STAGE(bufoff, gbase, voff) do { _Pragma("unroll") for (int _i = 0; _i < 2; ++_i) \
;         __builtin_amdgcn_global_load_lds((const unsigned*)((const char*)(gbase) + (voff)[_i]), (PG8_LAS unsigned*)(lds + (bufoff) + ldsw + _i * 8192), 16, 0, 0); } while (0)
; #define PG8_LDA(dst, b, h) do { _Pragma("unroll") for (int m = 0; m < 4; ++m) _Pragma("unroll") for (int k = 0; k < 2; ++k) dst[m][k] = *(const PG8_LAS bf16x8*)(lds + PG8_SA(b, h) + aoff + m * 2048 + k * 1024); } while (0)
; #define PG8_MMA(ai, bj, At, Bt) do { __builtin_amdgcn_s_setprio(1); _Pragma("unroll") for (int m = 0; m < 4; ++m) _Pragma("unroll") for (int n = 0; n < 2; ++n) _Pragma("unroll") for (int k = 0; k < 2; ++k) \
;         acc[ai][bj][m][n] = __builtin_amdgcn_mfma_f32_16x16x32_bf16(Bt[n][k], At[m][k], acc[ai][bj][m][n], 0, 0, 0); __builtin_amdgcn_s_setprio(0); } while (0)
; #define PG8_WAIT_V(n) asm volatile("s_waitcnt vmcnt(" #n ")" ::: "memory")
; #define PG8_WAIT_L(n) asm volatile("s_waitcnt lgkmcnt(" #n ")" ::: "memory")
; #define PG8_BAR __builtin_amdgcn_s_barrier()
; #define PG8_SCHED __builtin_amdgcn_sched_barrier(0)
; template <class Epi, class Sched, bool ALIGN_EPI = false, bool SP2 = false>
; __device__ __forceinline__ void gemm_phase(PG8_LAS unsigned char* lds, const Gemm g, const Sched& S, const Epi& E) {
;     ...
;             PG8_LDA(At, 0, 1); PG8_STAGE(PG8_SB(0, 0), b2, voffB); PG8_STAGE(PG8_SB(0, 1), b2 + hstep, voffB); PG8_STAGE(PG8_SA(0, 0), a2, voffA);
;             PG8_WAIT_V(8); PG8_WAIT_L(0); PG8_BAR; PG8_MMA(1, 0, At, B0); PG8_MMA(1, 1, At, B1); PG8_BAR; PG8_SCHED;
	s_barrier
	s_add_i32 s48, s48, s2
	v_lshl_add_u64 v[146:147], s[26:27], 0, v[132:133]
	s_mov_b32 m0, s48
	ds_read_b128 v[182:185], v153 offset:16384
	ds_read_b128 v[186:189], v153 offset:17408
	ds_read_b128 v[202:205], v153 offset:18432
	ds_read_b128 v[206:209], v153 offset:19456
	ds_read_b128 v[210:213], v153 offset:20480
	ds_read_b128 v[214:217], v153 offset:21504
	ds_read_b128 v[232:235], v153 offset:22528
	ds_read_b128 v[236:239], v153 offset:23552
	global_load_lds_dwordx4 v[146:147], off
	s_add_i32 m0, s48, 0x2000
	s_add_u32 s48, s26, 0x40000
	v_lshl_add_u64 v[190:191], s[26:27], 0, v[128:129]
	s_addc_u32 s49, s27, 0
	s_add_i32 s50, s50, s2
	global_load_lds_dwordx4 v[190:191], off
	v_lshl_add_u64 v[196:197], s[48:49], 0, v[132:133]
	s_mov_b32 m0, s50
	v_lshl_add_u64 v[198:199], s[28:29], 0, v[130:131]
	global_load_lds_dwordx4 v[196:197], off
	v_lshl_add_u64 v[196:197], s[48:49], 0, v[128:129]
	s_add_i32 m0, s50, 0x2000
	s_nop 0
	global_load_lds_dwordx4 v[196:197], off
	v_lshl_add_u64 v[196:197], s[28:29], 0, v[134:135]
	s_mov_b32 m0, s31
	s_nop 0
	global_load_lds_dwordx4 v[196:197], off
	s_mov_b32 m0, s34
	s_nop 0
	global_load_lds_dwordx4 v[198:199], off
	s_waitcnt vmcnt(8)
	s_waitcnt lgkmcnt(0)
	s_barrier

; #define PG8_MMA(ai, bj, At, Bt) do { __builtin_amdgcn_s_setprio(1); _Pragma("unroll") for (int m = 0; m < 4; ++m) _Pragma("unroll") for (int n = 0; n < 2; ++n) _Pragma("unroll") for (int k = 0; k < 2; ++k) \
;         acc[ai][bj][m][n] = __builtin_amdgcn_mfma_f32_16x16x32_bf16(Bt[n][k], At[m][k], acc[ai][bj][m][n], 0, 0, 0); __builtin_amdgcn_s_setprio(0); } while (0)
; #define PG8_WAIT_V(n) asm volatile("s_waitcnt vmcnt(" #n ")" ::: "memory")
; #define PG8_WAIT_L(n) asm volatile("s_waitcnt lgkmcnt(" #n ")" ::: "memory")
; #define PG8_BAR __builtin_amdgcn_s_barrier()
; #define PG8_SCHED __builtin_amdgcn_sched_barrier(0)
; template <class Epi, class Sched, bool ALIGN_EPI = false, bool SP2 = false>
; __device__ __forceinline__ void gemm_phase(PG8_LAS unsigned char* lds, const Gemm g, const Sched& S, const Epi& E) {
;     ...
;             PG8_WAIT_V(8); PG8_WAIT_L(0); PG8_BAR; PG8_MMA(1, 0, At, B0); PG8_MMA(1, 1, At, B1); PG8_BAR; PG8_SCHED;
	s_waitcnt lgkmcnt(0)
	v_mfma_f32_16x16x32_bf16 v[60:63], v[142:145], v[182:185], v[60:63]
	v_mfma_f32_16x16x32_bf16 v[52:55], v[158:161], v[182:185], v[52:55]
	v_mfma_f32_16x16x32_bf16 v[44:47], v[142:145], v[202:205], v[44:47]
	v_mfma_f32_16x16x32_bf16 v[36:39], v[158:161], v[202:205], v[36:39]
	v_mfma_f32_16x16x32_bf16 v[28:31], v[142:145], v[210:213], v[28:31]
	v_mfma_f32_16x16x32_bf16 v[20:23], v[158:161], v[210:213], v[20:23]
	v_mfma_f32_16x16x32_bf16 v[12:15], v[142:145], v[232:235], v[12:15]
	v_mfma_f32_16x16x32_bf16 v[4:7], v[158:161], v[232:235], v[4:7]
	v_mfma_f32_16x16x32_bf16 v[60:63], v[154:157], v[186:189], v[60:63]
	v_mfma_f32_16x16x32_bf16 v[52:55], v[162:165], v[186:189], v[52:55]
	v_mfma_f32_16x16x32_bf16 v[44:47], v[154:157], v[206:209], v[44:47]
	v_mfma_f32_16x16x32_bf16 v[36:39], v[162:165], v[206:209], v[36:39]
	v_mfma_f32_16x16x32_bf16 v[28:31], v[154:157], v[214:217], v[28:31]
	v_mfma_f32_16x16x32_bf16 v[20:23], v[162:165], v[214:217], v[20:23]
	v_mfma_f32_16x16x32_bf16 v[12:15], v[154:157], v[236:239], v[12:15]
	v_mfma_f32_16x16x32_bf16 v[4:7], v[162:165], v[236:239], v[4:7]


; #define PG8_MMA(ai, bj, At, Bt) do { __builtin_amdgcn_s_setprio(1); _Pragma("unroll") for (int m = 0; m < 4; ++m) _Pragma("unroll") for (int n = 0; n < 2; ++n) _Pragma("unroll") for (int k = 0; k < 2; ++k) \
;         acc[ai][bj][m][n] = __builtin_amdgcn_mfma_f32_16x16x32_bf16(Bt[n][k], At[m][k], acc[ai][bj][m][n], 0, 0, 0); __builtin_amdgcn_s_setprio(0); } while (0)
; #define PG8_WAIT_V(n) asm volatile("s_waitcnt vmcnt(" #n ")" ::: "memory")
; #define PG8_WAIT_L(n) asm volatile("s_waitcnt lgkmcnt(" #n ")" ::: "memory")
; #define PG8_BAR __builtin_amdgcn_s_barrier()
; #define PG8_SCHED __builtin_amdgcn_sched_barrier(0)
; template <class Epi, class Sched, bool ALIGN_EPI = false, bool SP2 = false>
; __device__ __forceinline__ void gemm_phase(PG8_LAS unsigned char* lds, const Gemm g, const Sched& S, const Epi& E) {
;     ...
;             PG8_WAIT_V(8); PG8_WAIT_L(0); PG8_BAR; PG8_MMA(1, 0, At, B0); PG8_MMA(1, 1, At, B1); PG8_BAR; PG8_SCHED;
	v_mfma_f32_16x16x32_bf16 v[56:59], v[166:169], v[182:185], v[56:59]
	v_mfma_f32_16x16x32_bf16 v[48:51], v[174:177], v[182:185], v[48:51]
	v_mfma_f32_16x16x32_bf16 v[40:43], v[166:169], v[202:205], v[40:43]
	v_mfma_f32_16x16x32_bf16 v[32:35], v[174:177], v[202:205], v[32:35]
	v_mfma_f32_16x16x32_bf16 v[24:27], v[166:169], v[210:213], v[24:27]
	v_mfma_f32_16x16x32_bf16 v[16:19], v[174:177], v[210:213], v[16:19]
	v_mfma_f32_16x16x32_bf16 v[8:11], v[166:169], v[232:235], v[8:11]
	v_mfma_f32_16x16x32_bf16 v[0:3], v[174:177], v[232:235], v[0:3]
	v_mfma_f32_16x16x32_bf16 v[56:59], v[170:173], v[186:189], v[56:59]
	v_mfma_f32_16x16x32_bf16 v[48:51], v[178:181], v[186:189], v[48:51]
	v_mfma_f32_16x16x32_bf16 v[40:43], v[170:173], v[206:209], v[40:43]
	v_mfma_f32_16x16x32_bf16 v[32:35], v[178:181], v[206:209], v[32:35]
	v_mfma_f32_16x16x32_bf16 v[24:27], v[170:173], v[214:217], v[24:27]
	v_mfma_f32_16x16x32_bf16 v[16:19], v[178:181], v[214:217], v[16:19]
	v_mfma_f32_16x16x32_bf16 v[8:11], v[170:173], v[236:239], v[8:11]
	v_mfma_f32_16x16x32_bf16 v[0:3], v[178:181], v[236:239], v[0:3]

; #define PG8_STAGE(bufoff, gbase, voff) do { _Pragma("unroll") for (int _i = 0; _i < 2; ++_i) \
;         __builtin_amdgcn_global_load_lds((const unsigned*)((const char*)(gbase) + (voff)[_i]), (PG8_LAS unsigned*)(lds + (bufoff) + ldsw + _i * 8192), 16, 0, 0); } while (0)
; #define PG8_LDA(dst, b, h) do { _Pragma("unroll") for (int m = 0; m < 4; ++m) _Pragma("unroll") for (int k = 0; k < 2; ++k) dst[m][k] = *(const PG8_LAS bf16x8*)(lds + PG8_SA(b, h) + aoff + m * 2048 + k * 1024); } while (0)
; #define PG8_LDB(dst, b, h) do { _Pragma("unroll") for (int n = 0; n < 2; ++n) _Pragma("unroll") for (int k = 0; k < 2; ++k) dst[n][k] = *(const PG8_LAS bf16x8*)(lds + PG8_SB(b, h) + boff + n * 2048 + k * 1024); } while (0)
; #define PG8_MMA(ai, bj, At, Bt) do { __builtin_amdgcn_s_setprio(1); _Pragma("unroll") for (int m = 0; m < 4; ++m) _Pragma("unroll") for (int n = 0; n < 2; ++n) _Pragma("unroll") for (int k = 0; k < 2; ++k) \
;         acc[ai][bj][m][n] = __builtin_amdgcn_mfma_f32_16x16x32_bf16(Bt[n][k], At[m][k], acc[ai][bj][m][n], 0, 0, 0); __builtin_amdgcn_s_setprio(0); } while (0)
; #define PG8_WAIT_V(n) asm volatile("s_waitcnt vmcnt(" #n ")" ::: "memory")
; #define PG8_WAIT_L(n) asm volatile("s_waitcnt lgkmcnt(" #n ")" ::: "memory")
; #define PG8_BAR __builtin_amdgcn_s_barrier()
; #define PG8_SCHED __builtin_amdgcn_sched_barrier(0)
; template <class Epi, class Sched, bool ALIGN_EPI = false, bool SP2 = false>
; __device__ __forceinline__ void gemm_phase(PG8_LAS unsigned char* lds, const Gemm g, const Sched& S, const Epi& E) {
;     ...
;             PG8_LDB(B0, 1, 0); PG8_LDB(B1, 1, 1); PG8_SCHED; PG8_LDA(At, 1, 0); PG8_STAGE(PG8_SA(0, 1), a2 + hstep, voffA);
;             PG8_WAIT_V(8); PG8_WAIT_L(0); PG8_BAR; PG8_MMA(0, 0, At, B0); PG8_MMA(0, 1, At, B1); PG8_BAR; PG8_SCHED;
	s_barrier
	s_add_i32 s48, 0, 0x18000
	v_add_u32_e32 v140, s48, v148
	s_add_i32 s49, 0, 0x1c000
	ds_read_b128 v[142:145], v140
	ds_read_b128 v[154:157], v140 offset:1024
	ds_read_b128 v[158:161], v140 offset:2048
	ds_read_b128 v[162:165], v140 offset:3072
	v_add_u32_e32 v140, s49, v148
	ds_read_b128 v[166:169], v140
	ds_read_b128 v[170:173], v140 offset:1024
	ds_read_b128 v[174:177], v140 offset:2048
	ds_read_b128 v[178:181], v140 offset:3072
	s_add_u32 s28, s28, 0x40000
	s_addc_u32 s29, s29, 0
	s_mov_b32 m0, s35
	v_lshl_add_u64 v[220:221], s[28:29], 0, v[134:135]
	ds_read_b128 v[182:185], v153 offset:32768
	ds_read_b128 v[186:189], v153 offset:33792
	ds_read_b128 v[202:205], v153 offset:34816
	ds_read_b128 v[206:209], v153 offset:35840
	ds_read_b128 v[210:213], v153 offset:36864
	ds_read_b128 v[214:217], v153 offset:37888
	ds_read_b128 v[232:235], v153 offset:38912
	ds_read_b128 v[236:239], v153 offset:39936
	global_load_lds_dwordx4 v[220:221], off
	v_lshl_add_u64 v[220:221], s[28:29], 0, v[130:131]
	s_mov_b32 m0, s36
	s_nop 0
	global_load_lds_dwordx4 v[220:221], off
	s_waitcnt vmcnt(8)
	s_waitcnt lgkmcnt(0)
	s_barrier

; #define PG8_MMA(ai, bj, At, Bt) do { __builtin_amdgcn_s_setprio(1); _Pragma("unroll") for (int m = 0; m < 4; ++m) _Pragma("unroll") for (int n = 0; n < 2; ++n) _Pragma("unroll") for (int k = 0; k < 2; ++k) \
;         acc[ai][bj][m][n] = __builtin_amdgcn_mfma_f32_16x16x32_bf16(Bt[n][k], At[m][k], acc[ai][bj][m][n], 0, 0, 0); __builtin_amdgcn_s_setprio(0); } while (0)
; #define PG8_WAIT_V(n) asm volatile("s_waitcnt vmcnt(" #n ")" ::: "memory")
; #define PG8_WAIT_L(n) asm volatile("s_waitcnt lgkmcnt(" #n ")" ::: "memory")
; #define PG8_BAR __builtin_amdgcn_s_barrier()
; #define PG8_SCHED __builtin_amdgcn_sched_barrier(0)
; template <class Epi, class Sched, bool ALIGN_EPI = false, bool SP2 = false>
; __device__ __forceinline__ void gemm_phase(PG8_LAS unsigned char* lds, const Gemm g, const Sched& S, const Epi& E) {
;     ...
;             PG8_WAIT_V(8); PG8_WAIT_L(0); PG8_BAR; PG8_MMA(0, 0, At, B0); PG8_MMA(0, 1, At, B1); PG8_BAR; PG8_SCHED;
	s_waitcnt lgkmcnt(0)
	v_mfma_f32_16x16x32_bf16 v[124:127], v[142:145], v[182:185], v[124:127]
	v_mfma_f32_16x16x32_bf16 v[116:119], v[158:161], v[182:185], v[116:119]
	v_mfma_f32_16x16x32_bf16 v[108:111], v[142:145], v[202:205], v[108:111]
	v_mfma_f32_16x16x32_bf16 v[100:103], v[158:161], v[202:205], v[100:103]
	v_mfma_f32_16x16x32_bf16 v[92:95], v[142:145], v[210:213], v[92:95]
	v_mfma_f32_16x16x32_bf16 v[84:87], v[158:161], v[210:213], v[84:87]
	v_mfma_f32_16x16x32_bf16 v[76:79], v[142:145], v[232:235], v[76:79]
	v_mfma_f32_16x16x32_bf16 v[68:71], v[158:161], v[232:235], v[68:71]
	v_mfma_f32_16x16x32_bf16 v[124:127], v[154:157], v[186:189], v[124:127]
	v_mfma_f32_16x16x32_bf16 v[116:119], v[162:165], v[186:189], v[116:119]
	v_mfma_f32_16x16x32_bf16 v[108:111], v[154:157], v[206:209], v[108:111]
	v_mfma_f32_16x16x32_bf16 v[100:103], v[162:165], v[206:209], v[100:103]
	v_mfma_f32_16x16x32_bf16 v[92:95], v[154:157], v[214:217], v[92:95]
	v_mfma_f32_16x16x32_bf16 v[84:87], v[162:165], v[214:217], v[84:87]
	v_mfma_f32_16x16x32_bf16 v[76:79], v[154:157], v[236:239], v[76:79]
	v_mfma_f32_16x16x32_bf16 v[68:71], v[162:165], v[236:239], v[68:71]


; #define PG8_MMA(ai, bj, At, Bt) do { __builtin_amdgcn_s_setprio(1); _Pragma("unroll") for (int m = 0; m < 4; ++m) _Pragma("unroll") for (int n = 0; n < 2; ++n) _Pragma("unroll") for (int k = 0; k < 2; ++k) \
;         acc[ai][bj][m][n] = __builtin_amdgcn_mfma_f32_16x16x32_bf16(Bt[n][k], At[m][k], acc[ai][bj][m][n], 0, 0, 0); __builtin_amdgcn_s_setprio(0); } while (0)
; #define PG8_WAIT_V(n) asm volatile("s_waitcnt vmcnt(" #n ")" ::: "memory")
; #define PG8_WAIT_L(n) asm volatile("s_waitcnt lgkmcnt(" #n ")" ::: "memory")
; #define PG8_BAR __builtin_amdgcn_s_barrier()
; #define PG8_SCHED __builtin_amdgcn_sched_barrier(0)
; template <class Epi, class Sched, bool ALIGN_EPI = false, bool SP2 = false>
; __device__ __forceinline__ void gemm_phase(PG8_LAS unsigned char* lds, const Gemm g, const Sched& S, const Epi& E) {
;     ...
;             PG8_WAIT_V(8); PG8_WAIT_L(0); PG8_BAR; PG8_MMA(0, 0, At, B0); PG8_MMA(0, 1, At, B1); PG8_BAR; PG8_SCHED;
	v_mfma_f32_16x16x32_bf16 v[120:123], v[166:169], v[182:185], v[120:123]
	v_mfma_f32_16x16x32_bf16 v[112:115], v[174:177], v[182:185], v[112:115]
	v_mfma_f32_16x16x32_bf16 v[104:107], v[166:169], v[202:205], v[104:107]
	v_mfma_f32_16x16x32_bf16 v[96:99], v[174:177], v[202:205], v[96:99]
	v_mfma_f32_16x16x32_bf16 v[88:91], v[166:169], v[210:213], v[88:91]
	v_mfma_f32_16x16x32_bf16 v[80:83], v[174:177], v[210:213], v[80:83]
	v_mfma_f32_16x16x32_bf16 v[72:75], v[166:169], v[232:235], v[72:75]
	v_mfma_f32_16x16x32_bf16 v[64:67], v[174:177], v[232:235], v[64:67]
	v_mfma_f32_16x16x32_bf16 v[120:123], v[170:173], v[186:189], v[120:123]
	v_mfma_f32_16x16x32_bf16 v[112:115], v[178:181], v[186:189], v[112:115]
	v_mfma_f32_16x16x32_bf16 v[104:107], v[170:173], v[206:209], v[104:107]
	v_mfma_f32_16x16x32_bf16 v[96:99], v[178:181], v[206:209], v[96:99]
	v_mfma_f32_16x16x32_bf16 v[88:91], v[170:173], v[214:217], v[88:91]
	v_mfma_f32_16x16x32_bf16 v[80:83], v[178:181], v[214:217], v[80:83]
	v_mfma_f32_16x16x32_bf16 v[72:75], v[170:173], v[236:239], v[72:75]
	v_mfma_f32_16x16x32_bf16 v[64:67], v[178:181], v[236:239], v[64:67]

; #define PG8_STAGE(bufoff, gbase, voff) do { _Pragma("unroll") for (int _i = 0; _i < 2; ++_i) \
;         __builtin_amdgcn_global_load_lds((const unsigned*)((const char*)(gbase) + (voff)[_i]), (PG8_LAS unsigned*)(lds + (bufoff) + ldsw + _i * 8192), 16, 0, 0); } while (0)
; #define PG8_LDA(dst, b, h) do { _Pragma("unroll") for (int m = 0; m < 4; ++m) _Pragma("unroll") for (int k = 0; k < 2; ++k) dst[m][k] = *(const PG8_LAS bf16x8*)(lds + PG8_SA(b, h) + aoff + m * 2048 + k * 1024); } while (0)
; #define PG8_MMA(ai, bj, At, Bt) do { __builtin_amdgcn_s_setprio(1); _Pragma("unroll") for (int m = 0; m < 4; ++m) _Pragma("unroll") for (int n = 0; n < 2; ++n) _Pragma("unroll") for (int k = 0; k < 2; ++k) \
;         acc[ai][bj][m][n] = __builtin_amdgcn_mfma_f32_16x16x32_bf16(Bt[n][k], At[m][k], acc[ai][bj][m][n], 0, 0, 0); __builtin_amdgcn_s_setprio(0); } while (0)
; #define PG8_WAIT_V(n) asm volatile("s_waitcnt vmcnt(" #n ")" ::: "memory")
; #define PG8_WAIT_L(n) asm volatile("s_waitcnt lgkmcnt(" #n ")" ::: "memory")
; #define PG8_BAR __builtin_amdgcn_s_barrier()
; #define PG8_SCHED __builtin_amdgcn_sched_barrier(0)
; template <class Epi, class Sched, bool ALIGN_EPI = false, bool SP2 = false>
; __device__ __forceinline__ void gemm_phase(PG8_LAS unsigned char* lds, const Gemm g, const Sched& S, const Epi& E) {
;     ...
;             PG8_LDA(At, 1, 1); PG8_STAGE(PG8_SB(1, 0), b3, voffB); PG8_STAGE(PG8_SB(1, 1), b3 + hstep, voffB); PG8_STAGE(PG8_SA(1, 0), a3, voffA);
;             PG8_WAIT_V(8); PG8_WAIT_L(0); PG8_BAR; PG8_MMA(1, 0, At, B0); PG8_MMA(1, 1, At, B1); PG8_BAR; PG8_SCHED;
	s_barrier
	s_add_i32 s28, s48, s2
	v_lshl_add_u64 v[146:147], v[146:147], 0, s[0:1]
	s_mov_b32 m0, s28
	ds_read_b128 v[182:185], v153 offset:49152
	ds_read_b128 v[186:189], v153 offset:50176
	ds_read_b128 v[202:205], v153 offset:51200
	ds_read_b128 v[206:209], v153 offset:52224
	ds_read_b128 v[210:213], v153 offset:53248
	ds_read_b128 v[214:217], v153 offset:54272
	ds_read_b128 v[232:235], v153 offset:55296
	ds_read_b128 v[236:239], v153 offset:56320
	global_load_lds_dwordx4 v[146:147], off
	s_add_i32 m0, s28, 0x2000
	s_add_u32 s26, s26, 0x40080
	v_lshl_add_u64 v[146:147], v[190:191], 0, s[0:1]
	s_addc_u32 s27, s27, 0
	s_add_i32 s28, s49, s2
	global_load_lds_dwordx4 v[146:147], off
	v_lshl_add_u64 v[146:147], s[26:27], 0, v[132:133]
	s_mov_b32 m0, s28
	s_nop 0
	global_load_lds_dwordx4 v[146:147], off
	v_lshl_add_u64 v[146:147], s[26:27], 0, v[128:129]
	s_add_i32 m0, s28, 0x2000
	s_nop 0
	global_load_lds_dwordx4 v[146:147], off
	v_lshl_add_u64 v[146:147], v[196:197], 0, s[0:1]
	s_mov_b32 m0, s37
	s_nop 0
	global_load_lds_dwordx4 v[146:147], off
	v_lshl_add_u64 v[146:147], v[198:199], 0, s[0:1]
	s_mov_b32 m0, s38
	s_nop 0
	global_load_lds_dwordx4 v[146:147], off
	s_waitcnt vmcnt(8)
	s_waitcnt lgkmcnt(0)
	s_barrier

; #define PG8_MMA(ai, bj, At, Bt) do { __builtin_amdgcn_s_setprio(1); _Pragma("unroll") for (int m = 0; m < 4; ++m) _Pragma("unroll") for (int n = 0; n < 2; ++n) _Pragma("unroll") for (int k = 0; k < 2; ++k) \
;         acc[ai][bj][m][n] = __builtin_amdgcn_mfma_f32_16x16x32_bf16(Bt[n][k], At[m][k], acc[ai][bj][m][n], 0, 0, 0); __builtin_amdgcn_s_setprio(0); } while (0)
; #define PG8_WAIT_V(n) asm volatile("s_waitcnt vmcnt(" #n ")" ::: "memory")
; #define PG8_WAIT_L(n) asm volatile("s_waitcnt lgkmcnt(" #n ")" ::: "memory")
; #define PG8_BAR __builtin_amdgcn_s_barrier()
; #define PG8_SCHED __builtin_amdgcn_sched_barrier(0)
; template <class Epi, class Sched, bool ALIGN_EPI = false, bool SP2 = false>
; __device__ __forceinline__ void gemm_phase(PG8_LAS unsigned char* lds, const Gemm g, const Sched& S, const Epi& E) {
;     ...
;             PG8_WAIT_V(8); PG8_WAIT_L(0); PG8_BAR; PG8_MMA(1, 0, At, B0); PG8_MMA(1, 1, At, B1); PG8_BAR; PG8_SCHED;
	s_waitcnt lgkmcnt(0)
	v_mfma_f32_16x16x32_bf16 v[60:63], v[142:145], v[182:185], v[60:63]
	v_mfma_f32_16x16x32_bf16 v[52:55], v[158:161], v[182:185], v[52:55]
	v_mfma_f32_16x16x32_bf16 v[44:47], v[142:145], v[202:205], v[44:47]
	v_mfma_f32_16x16x32_bf16 v[36:39], v[158:161], v[202:205], v[36:39]
	v_mfma_f32_16x16x32_bf16 v[28:31], v[142:145], v[210:213], v[28:31]
	v_mfma_f32_16x16x32_bf16 v[20:23], v[158:161], v[210:213], v[20:23]
	v_mfma_f32_16x16x32_bf16 v[12:15], v[142:145], v[232:235], v[12:15]
	v_mfma_f32_16x16x32_bf16 v[4:7], v[158:161], v[232:235], v[4:7]
	v_mfma_f32_16x16x32_bf16 v[60:63], v[154:157], v[186:189], v[60:63]
	v_mfma_f32_16x16x32_bf16 v[52:55], v[162:165], v[186:189], v[52:55]
	v_mfma_f32_16x16x32_bf16 v[44:47], v[154:157], v[206:209], v[44:47]
	v_mfma_f32_16x16x32_bf16 v[36:39], v[162:165], v[206:209], v[36:39]
	v_mfma_f32_16x16x32_bf16 v[28:31], v[154:157], v[214:217], v[28:31]
	v_mfma_f32_16x16x32_bf16 v[20:23], v[162:165], v[214:217], v[20:23]
	v_mfma_f32_16x16x32_bf16 v[12:15], v[154:157], v[236:239], v[12:15]
	v_mfma_f32_16x16x32_bf16 v[4:7], v[162:165], v[236:239], v[4:7]


; #define PG8_MMA(ai, bj, At, Bt) do { __builtin_amdgcn_s_setprio(1); _Pragma("unroll") for (int m = 0; m < 4; ++m) _Pragma("unroll") for (int n = 0; n < 2; ++n) _Pragma("unroll") for (int k = 0; k < 2; ++k) \
;         acc[ai][bj][m][n] = __builtin_amdgcn_mfma_f32_16x16x32_bf16(Bt[n][k], At[m][k], acc[ai][bj][m][n], 0, 0, 0); __builtin_amdgcn_s_setprio(0); } while (0)
; #define PG8_WAIT_V(n) asm volatile("s_waitcnt vmcnt(" #n ")" ::: "memory")
; #define PG8_WAIT_L(n) asm volatile("s_waitcnt lgkmcnt(" #n ")" ::: "memory")
; #define PG8_BAR __builtin_amdgcn_s_barrier()
; #define PG8_SCHED __builtin_amdgcn_sched_barrier(0)
; template <class Epi, class Sched, bool ALIGN_EPI = false, bool SP2 = false>
; __device__ __forceinline__ void gemm_phase(PG8_LAS unsigned char* lds, const Gemm g, const Sched& S, const Epi& E) {
;     ...
;             PG8_WAIT_V(8); PG8_WAIT_L(0); PG8_BAR; PG8_MMA(1, 0, At, B0); PG8_MMA(1, 1, At, B1); PG8_BAR; PG8_SCHED;
	v_mfma_f32_16x16x32_bf16 v[56:59], v[166:169], v[182:185], v[56:59]
	v_mfma_f32_16x16x32_bf16 v[48:51], v[174:177], v[182:185], v[48:51]
	v_mfma_f32_16x16x32_bf16 v[40:43], v[166:169], v[202:205], v[40:43]
	v_mfma_f32_16x16x32_bf16 v[32:35], v[174:177], v[202:205], v[32:35]
	v_mfma_f32_16x16x32_bf16 v[24:27], v[166:169], v[210:213], v[24:27]
	v_mfma_f32_16x16x32_bf16 v[16:19], v[174:177], v[210:213], v[16:19]
	v_mfma_f32_16x16x32_bf16 v[8:11], v[166:169], v[232:235], v[8:11]
	v_mfma_f32_16x16x32_bf16 v[0:3], v[174:177], v[232:235], v[0:3]
	v_mfma_f32_16x16x32_bf16 v[56:59], v[170:173], v[186:189], v[56:59]
	v_mfma_f32_16x16x32_bf16 v[48:51], v[178:181], v[186:189], v[48:51]
	v_mfma_f32_16x16x32_bf16 v[40:43], v[170:173], v[206:209], v[40:43]
	v_mfma_f32_16x16x32_bf16 v[32:35], v[178:181], v[206:209], v[32:35]
	v_mfma_f32_16x16x32_bf16 v[24:27], v[170:173], v[214:217], v[24:27]
	v_mfma_f32_16x16x32_bf16 v[16:19], v[178:181], v[214:217], v[16:19]
	v_mfma_f32_16x16x32_bf16 v[8:11], v[170:173], v[236:239], v[8:11]
	v_mfma_f32_16x16x32_bf16 v[0:3], v[178:181], v[236:239], v[0:3]

; #define PG8_BAR __builtin_amdgcn_s_barrier()
; template <class Epi, class Sched, bool ALIGN_EPI = false, bool SP2 = false>
; __device__ __forceinline__ void gemm_phase(PG8_LAS unsigned char* lds, const Gemm g, const Sched& S, const Epi& E) {
;     ...
;         for (int t = 0; t < nt; t += 2) {
;             const bool last = (t == nt - 2);
;     ...
;         if constexpr (ALIGN_EPI) { if (wr == 0) PG8_BAR; }
	s_barrier
	s_add_i32 s47, s47, 2
	s_add_u32 s8, s8, 0x100
	s_addc_u32 s9, s9, 0
	s_add_u32 s45, s45, 0x100
	s_addc_u32 s46, s46, 0
	s_cmp_gt_u32 s47, 13
	s_cbranch_scc0 .LBB0_161
	s_and_b64 vcc, exec, s[16:17]
	s_cbranch_vccz .LBB0_164
	s_barrier

; #define PG8_WAIT_V(n) asm volatile("s_waitcnt vmcnt(" #n ")" ::: "memory")
; #define PG8_BAR __builtin_amdgcn_s_barrier()
; template <class Epi, class Sched, bool ALIGN_EPI = false, bool SP2 = false>
; __device__ __forceinline__ void gemm_phase(PG8_LAS unsigned char* lds, const Gemm g, const Sched& S, const Epi& E) {
;     ...
;     PG8_WAIT_V(0);
;     if constexpr (!ALIGN_EPI) { if (wr == 0) PG8_BAR; }
;     PG8_BAR;
.LBB0_171:
	s_setprio 0
	s_waitcnt vmcnt(0)
	s_barrier
